# non-temporal hint on streamed-once traffic: residual loads in the xn phase, loads and output stores of the final RMSNorm phase
# speedup vs baseline: 1.0201x; 1.0201x over previous
.LBB0_340:
	v_writelane_b32 v255, s0, 45
	s_xor_b64 s[62:63], s[0:1], -1
	s_mul_i32 s68, s4, 0x2400
	v_writelane_b32 v255, s1, 46
	s_mov_b32 s0, s4
	v_writelane_b32 v255, s0, 47
	v_mov_b32_e32 v0, v252
	v_readlane_b32 s4, v253, 29
	v_writelane_b32 v255, s1, 48
	s_lshl_b64 s[0:1], s[68:69], 2
	s_add_u32 s66, s4, s0
	v_ashrrev_i32_e32 v1, 6, v0
	v_readlane_b32 s0, v253, 33
	v_readlane_b32 s5, v253, 30
	s_addc_u32 s67, s5, s1
	v_add_u32_e32 v18, s0, v1
	s_movk_i32 s0, 0x4000
	v_cmp_gt_i32_e32 vcc, s0, v18
	s_and_saveexec_b64 s[6:7], vcc
	s_cbranch_execz .LBB0_363
	v_readfirstlane_b32 s16, v18
	v_readlane_b32 s17, v255, 44
	v_lshlrev_b32_e32 v20, 4, v241
	v_lshlrev_b32_e32 v21, 3, v241
	v_lshlrev_b32_e32 v22, 2, v248
	v_lshlrev_b32_e32 v23, 2, v247
	v_lshlrev_b32_e32 v116, 2, v246
	v_lshlrev_b32_e32 v117, 2, v245
	v_lshlrev_b32_e32 v118, 2, v244
	v_lshlrev_b32_e32 v119, 2, v243
	v_readlane_b32 s4, v255, 47
	s_nop 0
	s_lshl_b32 s4, s4, 12
	s_add_u32 s14, s48, s4
	s_addc_u32 s15, s49, 0
	s_and_b64 vcc, exec, s[62:63]
	s_cbranch_vccnz .Lxn_l1
	s_cmp_lt_u32 s16, 0x2000
	s_cselect_b32 s8, s36, s38
	s_cselect_b32 s9, s37, s39
	s_and_b32 s4, s16, 0x1fff
	s_lshl_b32 s4, s4, 12
	s_add_u32 s8, s8, s4
	s_addc_u32 s9, s9, 0
	global_load_dwordx4 v[24:27], v20, s[8:9] nt
	global_load_dwordx4 v[28:31], v20, s[8:9] offset:1024 nt
	global_load_dwordx4 v[32:35], v20, s[8:9] offset:2048 nt
	global_load_dwordx4 v[36:39], v20, s[8:9] offset:3072 nt

.Lxn_idxd_l0a:
	s_add_u32 s22, s10, 0x1000
	s_addc_u32 s23, s11, 0
	global_load_dwordx4 v[56:59], v20, s[14:15]
	global_load_dwordx4 v[72:75], v20, s[22:23]
	global_load_dwordx4 v[88:91], v20, s[10:11]
	global_load_dwordx4 v[60:63], v20, s[14:15] offset:1024
	global_load_dwordx4 v[76:79], v20, s[22:23] offset:1024
	global_load_dwordx4 v[92:95], v20, s[10:11] offset:1024
	global_load_dwordx4 v[64:67], v20, s[14:15] offset:2048
	global_load_dwordx4 v[80:83], v20, s[22:23] offset:2048
	global_load_dwordx4 v[96:99], v20, s[10:11] offset:2048
	global_load_dwordx4 v[68:71], v20, s[14:15] offset:3072
	global_load_dwordx4 v[84:87], v20, s[22:23] offset:3072
	global_load_dwordx4 v[100:103], v20, s[10:11] offset:3072
	s_add_u32 s5, s16, s17
	s_cmp_lt_u32 s5, 0x4000
	s_cbranch_scc0 .Lxn_nonext_l0a
	s_mov_b32 s20, s5
	s_cmp_lt_u32 s20, 0x2000
	s_cselect_b32 s18, s36, s38
	s_cselect_b32 s19, s37, s39
	s_and_b32 s4, s20, 0x1fff
	s_lshl_b32 s4, s4, 12
	s_add_u32 s18, s18, s4
	s_addc_u32 s19, s19, 0
	global_load_dwordx4 v[40:43], v20, s[18:19] nt
	global_load_dwordx4 v[44:47], v20, s[18:19] offset:1024 nt
	global_load_dwordx4 v[48:51], v20, s[18:19] offset:2048 nt
	global_load_dwordx4 v[52:55], v20, s[18:19] offset:3072 nt
	s_waitcnt vmcnt(16)
	s_branch .Lxn_have_l0a

.Lxn_idxd_l0b:
	s_add_u32 s22, s10, 0x1000
	s_addc_u32 s23, s11, 0
	global_load_dwordx4 v[56:59], v20, s[14:15]
	global_load_dwordx4 v[72:75], v20, s[22:23]
	global_load_dwordx4 v[88:91], v20, s[10:11]
	global_load_dwordx4 v[60:63], v20, s[14:15] offset:1024
	global_load_dwordx4 v[76:79], v20, s[22:23] offset:1024
	global_load_dwordx4 v[92:95], v20, s[10:11] offset:1024
	global_load_dwordx4 v[64:67], v20, s[14:15] offset:2048
	global_load_dwordx4 v[80:83], v20, s[22:23] offset:2048
	global_load_dwordx4 v[96:99], v20, s[10:11] offset:2048
	global_load_dwordx4 v[68:71], v20, s[14:15] offset:3072
	global_load_dwordx4 v[84:87], v20, s[22:23] offset:3072
	global_load_dwordx4 v[100:103], v20, s[10:11] offset:3072
	s_add_u32 s5, s16, s17
	s_cmp_lt_u32 s5, 0x4000
	s_cbranch_scc0 .Lxn_nonext_l0b
	s_mov_b32 s20, s5
	s_cmp_lt_u32 s20, 0x2000
	s_cselect_b32 s18, s36, s38
	s_cselect_b32 s19, s37, s39
	s_and_b32 s4, s20, 0x1fff
	s_lshl_b32 s4, s4, 12
	s_add_u32 s18, s18, s4
	s_addc_u32 s19, s19, 0
	global_load_dwordx4 v[24:27], v20, s[18:19] nt
	global_load_dwordx4 v[28:31], v20, s[18:19] offset:1024 nt
	global_load_dwordx4 v[32:35], v20, s[18:19] offset:2048 nt
	global_load_dwordx4 v[36:39], v20, s[18:19] offset:3072 nt
	s_waitcnt vmcnt(16)
	s_branch .Lxn_have_l0b

.Lxn_l1:
	s_lshl_b32 s4, s16, 11
	s_add_u32 s8, s30, s4
	s_addc_u32 s9, s31, 0
	global_load_dwordx2 v[24:25], v21, s[8:9] nt
	global_load_dwordx2 v[28:29], v21, s[8:9] offset:512 nt
	global_load_dwordx2 v[32:33], v21, s[8:9] offset:1024 nt
	global_load_dwordx2 v[36:37], v21, s[8:9] offset:1536 nt

.Lxn_idxd_l1a:
	s_add_u32 s22, s10, 0x1000
	s_addc_u32 s23, s11, 0
	global_load_dwordx4 v[56:59], v20, s[14:15]
	global_load_dwordx4 v[72:75], v20, s[22:23]
	global_load_dwordx4 v[88:91], v20, s[10:11]
	global_load_dwordx4 v[60:63], v20, s[14:15] offset:1024
	global_load_dwordx4 v[76:79], v20, s[22:23] offset:1024
	global_load_dwordx4 v[92:95], v20, s[10:11] offset:1024
	global_load_dwordx4 v[64:67], v20, s[14:15] offset:2048
	global_load_dwordx4 v[80:83], v20, s[22:23] offset:2048
	global_load_dwordx4 v[96:99], v20, s[10:11] offset:2048
	global_load_dwordx4 v[68:71], v20, s[14:15] offset:3072
	global_load_dwordx4 v[84:87], v20, s[22:23] offset:3072
	global_load_dwordx4 v[100:103], v20, s[10:11] offset:3072
	s_add_u32 s5, s16, s17
	s_cmp_lt_u32 s5, 0x4000
	s_cbranch_scc0 .Lxn_nonext_l1a
	s_mov_b32 s20, s5
	s_lshl_b32 s4, s20, 11
	s_add_u32 s18, s30, s4
	s_addc_u32 s19, s31, 0
	global_load_dwordx2 v[40:41], v21, s[18:19] nt
	global_load_dwordx2 v[44:45], v21, s[18:19] offset:512 nt
	global_load_dwordx2 v[48:49], v21, s[18:19] offset:1024 nt
	global_load_dwordx2 v[52:53], v21, s[18:19] offset:1536 nt
	s_waitcnt vmcnt(16)
	s_branch .Lxn_have_l1a

.Lxn_idxd_l1b:
	s_add_u32 s22, s10, 0x1000
	s_addc_u32 s23, s11, 0
	global_load_dwordx4 v[56:59], v20, s[14:15]
	global_load_dwordx4 v[72:75], v20, s[22:23]
	global_load_dwordx4 v[88:91], v20, s[10:11]
	global_load_dwordx4 v[60:63], v20, s[14:15] offset:1024
	global_load_dwordx4 v[76:79], v20, s[22:23] offset:1024
	global_load_dwordx4 v[92:95], v20, s[10:11] offset:1024
	global_load_dwordx4 v[64:67], v20, s[14:15] offset:2048
	global_load_dwordx4 v[80:83], v20, s[22:23] offset:2048
	global_load_dwordx4 v[96:99], v20, s[10:11] offset:2048
	global_load_dwordx4 v[68:71], v20, s[14:15] offset:3072
	global_load_dwordx4 v[84:87], v20, s[22:23] offset:3072
	global_load_dwordx4 v[100:103], v20, s[10:11] offset:3072
	s_add_u32 s5, s16, s17
	s_cmp_lt_u32 s5, 0x4000
	s_cbranch_scc0 .Lxn_nonext_l1b
	s_mov_b32 s20, s5
	s_lshl_b32 s4, s20, 11
	s_add_u32 s18, s30, s4
	s_addc_u32 s19, s31, 0
	global_load_dwordx2 v[24:25], v21, s[18:19] nt
	global_load_dwordx2 v[28:29], v21, s[18:19] offset:512 nt
	global_load_dwordx2 v[32:33], v21, s[18:19] offset:1024 nt
	global_load_dwordx2 v[36:37], v21, s[18:19] offset:1536 nt
	s_waitcnt vmcnt(16)
	s_branch .Lxn_have_l1b

.LBB0_1664:
	v_ashrrev_i32_e32 v1, 31, v0
	v_lshlrev_b64 v[16:17], 11, v[0:1]
	v_lshl_add_u64 v[20:21], v[2:3], 0, v[16:17]
	global_load_dwordx2 v[22:23], v[20:21], off nt
	global_load_dwordx2 v[24:25], v[20:21], off offset:512 nt
	global_load_dwordx2 v[26:27], v[20:21], off offset:1024 nt
	global_load_dwordx2 v[28:29], v[20:21], off offset:1536 nt
	global_load_dwordx4 v[16:19], v[6:7], off
	s_waitcnt vmcnt(4)
	v_and_b32_e32 v21, 0xffff0000, v22
	s_waitcnt vmcnt(3)
	v_and_b32_e32 v31, 0xffff0000, v24
	v_lshlrev_b32_e32 v20, 16, v22
	v_lshlrev_b32_e32 v30, 16, v24
	s_waitcnt vmcnt(2)
	v_and_b32_e32 v33, 0xffff0000, v26
	s_waitcnt vmcnt(1)
	v_and_b32_e32 v35, 0xffff0000, v28
	v_mov_b32_e32 v38, v21
	v_mov_b32_e32 v39, v31
	v_lshlrev_b32_e32 v22, 16, v23
	v_lshlrev_b32_e32 v24, 16, v25
	v_lshlrev_b32_e32 v32, 16, v26
	v_lshlrev_b32_e32 v34, 16, v28
	v_mov_b32_e32 v36, v20
	v_mov_b32_e32 v37, v30
	v_mov_b32_e32 v46, v33
	v_mov_b32_e32 v47, v35
	v_pk_mul_f32 v[38:39], v[38:39], v[38:39]
	v_and_b32_e32 v23, 0xffff0000, v23
	v_and_b32_e32 v25, 0xffff0000, v25
	v_lshlrev_b32_e32 v26, 16, v27
	v_lshlrev_b32_e32 v28, 16, v29
	v_mov_b32_e32 v40, v22
	v_mov_b32_e32 v41, v24
	v_mov_b32_e32 v44, v32
	v_mov_b32_e32 v45, v34
	v_pk_mul_f32 v[46:47], v[46:47], v[46:47]
	v_pk_fma_f32 v[36:37], v[36:37], v[36:37], v[38:39]
	v_and_b32_e32 v27, 0xffff0000, v27
	v_and_b32_e32 v29, 0xffff0000, v29
	v_mov_b32_e32 v42, v23
	v_mov_b32_e32 v43, v25
	v_mov_b32_e32 v48, v26
	v_mov_b32_e32 v49, v28
	v_pk_fma_f32 v[38:39], v[44:45], v[44:45], v[46:47]
	v_pk_fma_f32 v[36:37], v[40:41], v[40:41], v[36:37]
	v_mov_b32_e32 v50, v27
	v_mov_b32_e32 v51, v29
	v_pk_fma_f32 v[38:39], v[48:49], v[48:49], v[38:39]
	v_pk_fma_f32 v[36:37], v[42:43], v[42:43], v[36:37]
	v_pk_fma_f32 v[38:39], v[50:51], v[50:51], v[38:39]
	v_add_f32_e32 v15, v36, v37
	v_add_f32_e32 v15, v15, v38
	v_add_f32_e32 v15, v15, v39
	ds_bpermute_b32 v36, v8, v15
	s_waitcnt lgkmcnt(0)
	v_add_f32_e32 v15, v15, v36
	ds_bpermute_b32 v36, v9, v15
	s_waitcnt lgkmcnt(0)
	v_add_f32_e32 v15, v15, v36
	ds_bpermute_b32 v36, v10, v15
	s_waitcnt lgkmcnt(0)
	v_add_f32_e32 v15, v15, v36
	ds_bpermute_b32 v36, v11, v15
	s_waitcnt lgkmcnt(0)
	v_add_f32_e32 v15, v15, v36
	ds_bpermute_b32 v36, v12, v15
	s_waitcnt lgkmcnt(0)
	v_add_f32_e32 v15, v15, v36
	ds_bpermute_b32 v36, v13, v15
	s_waitcnt lgkmcnt(0)
	v_add_f32_e32 v15, v15, v36
	v_fmamk_f32 v15, v15, 0x3a800000, v14
	v_mul_f32_e32 v36, 0x4b800000, v15
	v_cmp_gt_f32_e32 vcc, s2, v15
	s_nop 1
	v_cndmask_b32_e32 v15, v15, v36, vcc
	v_rsq_f32_e32 v15, v15
	v_lshlrev_b64 v[36:37], 12, v[0:1]
	v_lshl_add_u64 v[36:37], v[4:5], 0, v[36:37]
	v_add_u32_e32 v0, s44, v0
	v_mul_f32_e32 v1, 0x45800000, v15
	v_cndmask_b32_e32 v38, v15, v1, vcc
	v_pk_mul_f32 v[20:21], v[38:39], v[20:21] op_sel_hi:[0,1]
	v_pk_mul_f32 v[22:23], v[38:39], v[22:23] op_sel_hi:[0,1]
	s_waitcnt vmcnt(0)
	v_pk_mul_f32 v[16:17], v[16:17], v[20:21]
	v_pk_mul_f32 v[18:19], v[18:19], v[22:23]
	global_store_dwordx4 v[36:37], v[16:19], off nt
	global_load_dwordx4 v[16:19], v[6:7], off offset:1024
	v_pk_mul_f32 v[20:21], v[38:39], v[30:31] op_sel_hi:[0,1]
	v_pk_mul_f32 v[22:23], v[38:39], v[24:25] op_sel_hi:[0,1]
	v_cmp_lt_i32_e32 vcc, s3, v0
	s_or_b64 s[0:1], vcc, s[0:1]
	s_waitcnt vmcnt(0)
	v_pk_mul_f32 v[16:17], v[16:17], v[20:21]
	v_pk_mul_f32 v[18:19], v[18:19], v[22:23]
	global_store_dwordx4 v[36:37], v[16:19], off offset:1024 nt
	global_load_dwordx4 v[16:19], v[6:7], off offset:2048
	v_pk_mul_f32 v[20:21], v[38:39], v[32:33] op_sel_hi:[0,1]
	v_pk_mul_f32 v[22:23], v[38:39], v[26:27] op_sel_hi:[0,1]
	s_waitcnt vmcnt(0)
	v_pk_mul_f32 v[16:17], v[16:17], v[20:21]
	v_pk_mul_f32 v[18:19], v[18:19], v[22:23]
	global_store_dwordx4 v[36:37], v[16:19], off offset:2048 nt
	global_load_dwordx4 v[16:19], v[6:7], off offset:3072
	v_pk_mul_f32 v[20:21], v[38:39], v[34:35] op_sel_hi:[0,1]
	v_pk_mul_f32 v[22:23], v[38:39], v[28:29] op_sel_hi:[0,1]
	s_waitcnt vmcnt(0)
	v_pk_mul_f32 v[16:17], v[16:17], v[20:21]
	v_pk_mul_f32 v[18:19], v[18:19], v[22:23]
	global_store_dwordx4 v[36:37], v[16:19], off offset:3072 nt
	s_andn2_b64 exec, exec, s[0:1]
	s_cbranch_execnz .LBB0_1664
